# CA-q projection and cross attention run back to back in the same workgroup (same rows, same head): grid barrier between them replaced by vmcnt(0)+s_barrier+L1 invalidate
# baseline (speedup 1.0000x reference)
; #define BID opqs((int)blockIdx.x)
; template <int E1, int E2>
; DI void gemm_phase2(const GemmP& g1, const GemmP& g2, char* smem) {
;   const int n1 = g1.Mt * g1.Nt, n2 = g2.Mt * g2.Nt;
;   for (int L = BID; L < n1 + n2; L += gridDim.x) {
;     int pm, pn;
;     if (L < n1) { unit_of(L, g1.Mt, g1.Nt, pm, pn); gemm_unit<E1>(g1, pm, pn); }
;     else { unit_of(L - n1, g2.Mt, g2.Nt, pm, pn); gemm_unit<E2>(g2, pm, pn); }
; DI void run_phase(const Params& p, int ph, char* smem) {
;     ...
;     case 7: {
;       GemmP g1 = mk_gemm(XB, DM, (const u16*)(ws + O_CAQ + L * SZ_CA), DM, DM, 64, 2);
;       g1.Cb = (u16*)(ws + O_CQ); g1.ldc = 512;
;       gemm_phase2<EPI_BF16, EPI_BF16>(g1, gz, smem);
;     } break;
.LBB0_201:
	s_andn2_b64 vcc, exec, s[6:7]
	s_cbranch_vccnz .LBB0_463
	s_cmp_lt_i32 s62, 7
	s_mov_b64 s[6:7], -1
	s_cbranch_scc1 .LBB0_292
	s_cmp_gt_i32 s62, 7
	s_cbranch_scc0 .LBB0_213
	v_readlane_b32 s6, v254, 0
	s_and_b32 s7, s6, 7
	s_lshl_b32 s7, s7, 3
	s_bfe_u32 s8, s6, 0x30003
	s_add_i32 s7, s7, s8
	s_lshr_b32 s8, s6, 6
	s_lshr_b32 s6, s7, 5
	s_lshl_b32 s6, s6, 2
	s_or_b32 s8, s8, s6
	s_and_b32 s7, s7, 31
	s_lshl_b32 s7, s7, 3
	s_or_b32 s6, s7, s8
	s_cmpk_gt_i32 s6, 0xff
	s_cbranch_scc1 .LBB0_212
	s_add_u32 s7, s90, 0x3a480000
	s_addc_u32 s8, s91, 0
	s_add_u32 s9, s90, 0x3b480000
	s_addc_u32 s10, s91, 0
	s_ashr_i32 s13, s12, 31
	s_lshl_b64 s[14:15], s[12:13], 19
	s_add_u32 s14, s90, s14
	s_addc_u32 s15, s91, s15
	s_add_u32 s11, s14, 0x26700000
	s_addc_u32 s13, s15, 0
	s_add_u32 s14, s14, 0x26900000
	s_addc_u32 s15, s15, 0
	s_branch .LBB0_207

; DI unsigned xb_xcc_id() { return (unsigned)__builtin_amdgcn_s_getreg((3 << 11) | 20) & 0xFu; }
; __global__ void __launch_bounds__(512, 2) mega(Params p_unused, int ph_lo, int ph_hi, int coop) {
;     ...
;   for (int ph = ph_lo; ph < ph_hi; ++ph) {
;     const int sp = (ph - 1) % PH_PER_LAYER, L = (ph - 1) / PH_PER_LAYER;
;     const bool skip = (ph > 0) && (((L & 1) && (sp == 2 || sp == 3)) || sp == 6 || sp == 10 || sp == 13);
;     if (skip) continue;
;     ...
;     {
;       KParamsP kp = (KParamsP)__builtin_amdgcn_kernarg_segment_ptr();
;       asm volatile("" : "+s"(kp));
;       const Params lp = *kp;
;       run_phase(lp, ph, smem);
;       if (coop && ph + 1 < N_PHASES - 1) {
;         if (coop == 2) grid.sync();
;         else { XcdBarrier b; b.bar = (unsigned*)(lp.ws + O_BAR); b.x = xb_xcc_id(); b.st = st; xcd_barrier(b); }
.LBB0_1556:
	v_readlane_b32 s8, v254, 55
	v_readlane_b32 s9, v254, 56
	s_cmp_gt_i32 s8, 54
	v_readlane_b32 s8, v254, 26
	s_cselect_b64 s[6:7], -1, 0
	v_readlane_b32 s9, v254, 27
	s_or_b64 s[6:7], s[8:9], s[6:7]
	s_and_b64 vcc, exec, s[6:7]
	v_readlane_b32 s10, v254, 57
	v_readlane_b32 s11, v254, 58
	s_cbranch_vccz .LBB0_1557
.Lskipbar:
	s_getpc_b64 s[98:99]

; DI unsigned xb_add(unsigned* p, unsigned v) { return __hip_atomic_fetch_add(p, v, __ATOMIC_RELAXED, __HIP_MEMORY_SCOPE_AGENT); }
; DI unsigned xb_xcc_id() { return (unsigned)__builtin_amdgcn_s_getreg((3 << 11) | 20) & 0xFu; }
; DI void xcd_barrier(const XcdBarrier& b) {
;   asm volatile("s_waitcnt vmcnt(0)" ::: "memory");
;   __syncthreads();
;   if (threadIdx.x == 0) {
;     unsigned* bar = b.bar;
;     __builtin_amdgcn_s_waitcnt(0);
;     unsigned nloc = b.st[0], nx = b.st[1];
;     if (nloc == 0u) { xcd_barrier_complete(bar, b.x, nloc, nx); b.st[0] = nloc; b.st[1] = nx; }
;     const unsigned old = xb_add(&bar[XB_XSUB(b.x)], 1u);
; __global__ void __launch_bounds__(512, 2) mega(Params p_unused, int ph_lo, int ph_hi, int coop) {
;     ...
;       if (coop && ph + 1 < N_PHASES - 1) {
;         if (coop == 2) grid.sync();
;         else { XcdBarrier b; b.bar = (unsigned*)(lp.ws + O_BAR); b.x = xb_xcc_id(); b.st = st; xcd_barrier(b); }
.Lfuse78:
	s_waitcnt vmcnt(0)
	s_barrier
	buffer_inv sc1
	s_branch .Lskipbar
.LBB0_1557:
	v_readlane_b32 s8, v254, 55
	s_nop 3
	s_cmp_eq_u32 s8, 8
	s_cbranch_scc1 .Lfuse78
	s_cmp_eq_u32 s8, 22
	s_cbranch_scc1 .Lfuse78
	s_cmp_eq_u32 s8, 36
	s_cbranch_scc1 .Lfuse78
	s_cmp_eq_u32 s8, 50
	s_cbranch_scc1 .Lfuse78
	v_readlane_b32 s8, v254, 11
	v_readlane_b32 s9, v254, 12
	s_mov_b64 s[6:7], -1
	s_and_b64 vcc, exec, s[8:9]
	s_cbranch_vccz .LBB0_1611
	s_getreg_b32 s8, hwreg(HW_REG_XCC_ID, 0, 4)
	s_waitcnt vmcnt(0)
	s_waitcnt vmcnt(0)
	s_barrier
	s_mov_b64 s[6:7], exec
	v_readlane_b32 s10, v254, 7
	v_readlane_b32 s11, v254, 8
	s_and_b64 s[10:11], s[6:7], s[10:11]
	s_mov_b64 exec, s[10:11]
	s_cbranch_execz .LBB0_1610
	s_add_i32 s86, 0, 0x20000
	v_mov_b32_e32 v0, s86
	s_waitcnt vmcnt(0) expcnt(0) lgkmcnt(0)
	ds_read_b32 v3, v0
	v_readlane_b32 s9, v254, 52
	s_and_b32 s36, s8, 15
	s_waitcnt lgkmcnt(0)
	v_cmp_ne_u32_e32 vcc, 0, v3
	v_mov_b32_e32 v0, s9
	ds_read_b32 v2, v0
	s_cbranch_vccnz .LBB0_1574
	s_add_u32 s8, s90, 0x4f480200
	s_addc_u32 s9, s91, 0
	s_add_u32 s10, s90, 0x4f480400
	s_addc_u32 s11, s91, 0
	s_add_u32 s12, s90, 0x4f480500
	s_addc_u32 s13, s91, 0
	s_add_u32 s14, s90, 0x4f480600
	s_addc_u32 s15, s91, 0
	s_add_u32 s16, s90, 0x4f480700
	s_addc_u32 s17, s91, 0
	s_add_u32 s18, s90, 0x4f480800
	s_addc_u32 s19, s91, 0
	s_add_u32 s20, s90, 0x4f480900
	s_addc_u32 s21, s91, 0
	s_add_u32 s22, s90, 0x4f480a00
	s_addc_u32 s23, s91, 0
	s_add_u32 s24, s90, 0x4f480b00
	s_addc_u32 s25, s91, 0
	s_add_u32 s26, s90, 0x4f480c00
	s_addc_u32 s27, s91, 0
	s_add_u32 s38, s90, 0x4f480d00
	s_addc_u32 s39, s91, 0
	s_add_u32 s40, s90, 0x4f480e00
	s_addc_u32 s41, s91, 0
	s_add_u32 s42, s90, 0x4f480f00
	s_addc_u32 s43, s91, 0
	s_add_u32 s44, s90, 0x4f481000
	s_addc_u32 s45, s91, 0
	s_add_u32 s46, s90, 0x4f481100
	s_addc_u32 s47, s91, 0
	s_add_u32 s48, s90, 0x4f481200
	s_addc_u32 s49, s91, 0
	s_add_u32 s50, s90, 0x4f481300
	s_addc_u32 s51, s91, 0
	s_mov_b32 s87, 1
	s_branch .LBB0_1562
